# pooling pass: sample tasks too run from registers (15 history rows + 8 new rows loaded up front)
# speedup vs baseline: 1.0312x; 1.0268x over previous
; __device__ __forceinline__ void p3_pool(Frame& F) {
;     ...
;     for (int it = 0;; ++it) {
;         int tk2 = gw + it * NGW;
;         if (remap) { if (it == 1) { if ((int)blockIdx.x < 192 || F.wave >= 4) break; tk2 = 2048 + ((int)blockIdx.x - 192) * 4 + F.wave; } else if (it > 1) break; }
;         if (tk2 >= 2 * (NPR / 32 + DBATCH)) break;
;         const int tk = tk2 >> 1, c0 = (tk2 & 1) * 256 + lane * 4, w = 2 << (c0 >> 7);
;         const bool isP = tk < NPR / 32;
;         const int b = isP ? (tk >> 6) : (tk - NPR / 32), s0 = isP ? ((tk & 63) << 5) : 0, nsteps = isP ? 47 : 23;
;         const size_t mbase = isP ? (size_t)b * SEQ : (size_t)NPR + (size_t)b * 8;
.LBB0_523:
	s_and_b64 vcc, exec, s[8:9]
	s_cbranch_vccz .LBB0_516
	s_cmpk_lt_i32 s24, 0x900
	s_cbranch_scc0 .LBB0_516
	s_ashr_i32 s25, s24, 1
	s_cmpk_lt_i32 s25, 0x400
	s_cbranch_scc1 .Lp3f_entry
	s_branch .Lp3s_entry
	s_cmpk_gt_i32 s25, 0x3ff
	s_cselect_b64 s[6:7], -1, 0
	s_cmpk_lt_i32 s25, 0x400
	s_cselect_b64 s[8:9], -1, 0
	s_add_i32 s20, s25, 0xfffffc00
	s_and_b64 vcc, exec, s[6:7]
	s_cbranch_vccnz .LBB0_527
	s_ashr_i32 s10, s24, 7
	s_ashr_i32 s11, s10, 31
	s_lshl_b64 s[38:39], s[10:11], 11
	s_cbranch_execz .LBB0_528
	s_branch .LBB0_529

; #define U_LD(p) ({ const v2u w_ = *(const v2u*)(p); (f32x4){bflo(w_.x), bfhi(w_.x), bflo(w_.y), bfhi(w_.y)}; })
; __device__ __forceinline__ void p3_pool(Frame& F) {
;     ...
;         const int tk = tk2 >> 1, c0 = (tk2 & 1) * 256 + lane * 4, w = 2 << (c0 >> 7);
;         const bool isP = tk < NPR / 32;
;         const int b = isP ? (tk >> 6) : (tk - NPR / 32), s0 = isP ? ((tk & 63) << 5) : 0, nsteps = isP ? 47 : 23;
;         const size_t mbase = isP ? (size_t)b * SEQ : (size_t)NPR + (size_t)b * 8;
;         f32x4 S0 = (f32x4){0.f, 0.f, 0.f, 0.f};
; #pragma unroll 8
;         for (int i = 0; i < nsteps; ++i) {
;             const int s = s0 - 15 + i;
;             const int so = s - w;
;             f32x4 n0 = (f32x4){0.f, 0.f, 0.f, 0.f}, o0 = n0;
;             if (isP) {
;                 if (s >= 0) n0 = U_LD(U + (mbase + s) * 512 + c0);
;                 if (i >= w && so >= 0) o0 = U_LD(U + (mbase + so) * 512 + c0);
;             } else {
;                 if (s >= 0) n0 = U_LD(U + (mbase + s) * 512 + c0); else n0 = *(const f32x4*)(state_pool + ((size_t)b * 15 + (s + 15)) * 512 + c0);
;                 if (i >= w) { if (so >= 0) o0 = U_LD(U + (mbase + so) * 512 + c0); else o0 = *(const f32x4*)(state_pool + ((size_t)b * 15 + (so + 15)) * 512 + c0); }
;             }
;             S0 += n0 - o0;
;             if (i >= 15) {
.Lp3s_entry:
	s_waitcnt lgkmcnt(0)
	s_and_b32 s82, s24, 1
	s_add_i32 s83, s25, 0xfffffc00
	v_lshlrev_b32_e32 v36, 1, v32
	v_lshlrev_b32_e32 v37, 2, v32
	s_movk_i32 s87, 0x80
	v_cmp_le_u32_e64 s[94:95], s87, v32
	s_mul_i32 s84, s83, 0x7800
	s_lshl_b32 s85, s82, 10
	s_add_u32 s84, s84, s85
	s_add_u32 s88, s14, s84
	s_addc_u32 s89, s15, 0
	s_add_u32 s92, s16, s84
	s_addc_u32 s93, s17, 0
	s_lshl_b32 s85, s83, 3
	s_add_i32 s85, s85, 0x8000
	s_lshl_b32 s86, s82, 9
	s_lshl_b32 s84, s85, 10
	s_add_u32 s84, s84, s86
	s_add_u32 s90, s12, s84
	s_addc_u32 s91, s13, 0
	s_mul_i32 s86, s82, 0x1080000
	s_lshl_b32 s87, s85, 9
	s_add_u32 s86, s86, s87
	s_add_u32 s86, s86, 0xb400000
	s_add_u32 s84, s12, s86
	s_addc_u32 s85, s13, 0
	s_mov_b64 s[96:97], s[88:89]
	global_load_dwordx4 v[40:43], v37, s[96:97]
	global_load_dwordx4 v[44:47], v37, s[96:97] offset:2048
	s_add_u32 s96, s96, 0x1000
	s_addc_u32 s97, s97, 0
	global_load_dwordx4 v[48:51], v37, s[96:97]
	global_load_dwordx4 v[52:55], v37, s[96:97] offset:2048
	s_add_u32 s96, s96, 0x1000
	s_addc_u32 s97, s97, 0
	global_load_dwordx4 v[56:59], v37, s[96:97]
	global_load_dwordx4 v[60:63], v37, s[96:97] offset:2048
	s_add_u32 s96, s96, 0x1000
	s_addc_u32 s97, s97, 0
	global_load_dwordx4 v[64:67], v37, s[96:97]
	global_load_dwordx4 v[68:71], v37, s[96:97] offset:2048
	s_add_u32 s96, s96, 0x1000
	s_addc_u32 s97, s97, 0
	global_load_dwordx4 v[72:75], v37, s[96:97]
	global_load_dwordx4 v[76:79], v37, s[96:97] offset:2048
	s_add_u32 s96, s96, 0x1000
	s_addc_u32 s97, s97, 0
	global_load_dwordx4 v[80:83], v37, s[96:97]
	global_load_dwordx4 v[84:87], v37, s[96:97] offset:2048
	s_add_u32 s96, s96, 0x1000
	s_addc_u32 s97, s97, 0
	global_load_dwordx4 v[88:91], v37, s[96:97]
	global_load_dwordx4 v[92:95], v37, s[96:97] offset:2048
	s_add_u32 s96, s96, 0x1000
	s_addc_u32 s97, s97, 0
	global_load_dwordx4 v[96:99], v37, s[96:97]
	s_mov_b64 s[96:97], s[90:91]
	global_load_dwordx2 v[100:101], v36, s[96:97]
	global_load_dwordx2 v[102:103], v36, s[96:97] offset:1024
	global_load_dwordx2 v[104:105], v36, s[96:97] offset:2048
	global_load_dwordx2 v[106:107], v36, s[96:97] offset:3072
	s_add_u32 s96, s96, 0x1000
	s_addc_u32 s97, s97, 0
	global_load_dwordx2 v[108:109], v36, s[96:97]
	global_load_dwordx2 v[110:111], v36, s[96:97] offset:1024
	global_load_dwordx2 v[112:113], v36, s[96:97] offset:2048
	global_load_dwordx2 v[114:115], v36, s[96:97] offset:3072
	s_cmp_eq_u32 s82, 0
	s_cbranch_scc0 .Lp3s_h1
	v_mov_b32_e32 v140, 0
	v_mov_b32_e32 v141, 0
	v_mov_b32_e32 v142, 0
	v_mov_b32_e32 v143, 0
	v_mov_b32_e32 v166, 0
	v_mov_b32_e32 v167, 0
	v_mov_b32_e32 v168, 0
	v_mov_b32_e32 v169, 0
	v_mov_b32_e32 v144, 0x3f000000
	v_mov_b32_e32 v145, 0x3e800000
	v_cndmask_b32_e64 v164, v144, v145, s[94:95]
	s_waitcnt vmcnt(22)
	v_pk_add_f32 v[140:141], v[140:141], v[40:41]
	v_pk_add_f32 v[142:143], v[142:143], v[42:43]
	s_waitcnt vmcnt(21)
	v_pk_add_f32 v[140:141], v[140:141], v[44:45]
	v_pk_add_f32 v[142:143], v[142:143], v[46:47]
	s_waitcnt vmcnt(20)
	v_cndmask_b32_e64 v150, v40, v166, s[94:95]
	v_cndmask_b32_e64 v151, v41, v167, s[94:95]
	v_cndmask_b32_e64 v152, v42, v168, s[94:95]
	v_cndmask_b32_e64 v153, v43, v169, s[94:95]
	v_pk_add_f32 v[154:155], v[48:49], v[150:151] neg_lo:[0,1] neg_hi:[0,1]
	v_pk_add_f32 v[156:157], v[50:51], v[152:153] neg_lo:[0,1] neg_hi:[0,1]
	v_pk_add_f32 v[140:141], v[140:141], v[154:155]
	v_pk_add_f32 v[142:143], v[142:143], v[156:157]
	s_waitcnt vmcnt(19)
	v_cndmask_b32_e64 v150, v44, v166, s[94:95]
	v_cndmask_b32_e64 v151, v45, v167, s[94:95]
	v_cndmask_b32_e64 v152, v46, v168, s[94:95]
	v_cndmask_b32_e64 v153, v47, v169, s[94:95]
	v_pk_add_f32 v[154:155], v[52:53], v[150:151] neg_lo:[0,1] neg_hi:[0,1]
	v_pk_add_f32 v[156:157], v[54:55], v[152:153] neg_lo:[0,1] neg_hi:[0,1]
	v_pk_add_f32 v[140:141], v[140:141], v[154:155]
	v_pk_add_f32 v[142:143], v[142:143], v[156:157]
	s_waitcnt vmcnt(18)
	v_cndmask_b32_e64 v150, v48, v40, s[94:95]
	v_cndmask_b32_e64 v151, v49, v41, s[94:95]
	v_cndmask_b32_e64 v152, v50, v42, s[94:95]
	v_cndmask_b32_e64 v153, v51, v43, s[94:95]
	v_pk_add_f32 v[154:155], v[56:57], v[150:151] neg_lo:[0,1] neg_hi:[0,1]
	v_pk_add_f32 v[156:157], v[58:59], v[152:153] neg_lo:[0,1] neg_hi:[0,1]
	v_pk_add_f32 v[140:141], v[140:141], v[154:155]
	v_pk_add_f32 v[142:143], v[142:143], v[156:157]
	s_waitcnt vmcnt(17)
	v_cndmask_b32_e64 v150, v52, v44, s[94:95]
	v_cndmask_b32_e64 v151, v53, v45, s[94:95]
	v_cndmask_b32_e64 v152, v54, v46, s[94:95]
	v_cndmask_b32_e64 v153, v55, v47, s[94:95]
	v_pk_add_f32 v[154:155], v[60:61], v[150:151] neg_lo:[0,1] neg_hi:[0,1]
	v_pk_add_f32 v[156:157], v[62:63], v[152:153] neg_lo:[0,1] neg_hi:[0,1]
	v_pk_add_f32 v[140:141], v[140:141], v[154:155]
	v_pk_add_f32 v[142:143], v[142:143], v[156:157]
	s_waitcnt vmcnt(16)
	v_cndmask_b32_e64 v150, v56, v48, s[94:95]
	v_cndmask_b32_e64 v151, v57, v49, s[94:95]
	v_cndmask_b32_e64 v152, v58, v50, s[94:95]
	v_cndmask_b32_e64 v153, v59, v51, s[94:95]
	v_pk_add_f32 v[154:155], v[64:65], v[150:151] neg_lo:[0,1] neg_hi:[0,1]
	v_pk_add_f32 v[156:157], v[66:67], v[152:153] neg_lo:[0,1] neg_hi:[0,1]
	v_pk_add_f32 v[140:141], v[140:141], v[154:155]
	v_pk_add_f32 v[142:143], v[142:143], v[156:157]
	s_waitcnt vmcnt(15)
	v_cndmask_b32_e64 v150, v60, v52, s[94:95]
	v_cndmask_b32_e64 v151, v61, v53, s[94:95]
	v_cndmask_b32_e64 v152, v62, v54, s[94:95]
	v_cndmask_b32_e64 v153, v63, v55, s[94:95]
	v_pk_add_f32 v[154:155], v[68:69], v[150:151] neg_lo:[0,1] neg_hi:[0,1]
	v_pk_add_f32 v[156:157], v[70:71], v[152:153] neg_lo:[0,1] neg_hi:[0,1]
	v_pk_add_f32 v[140:141], v[140:141], v[154:155]
	v_pk_add_f32 v[142:143], v[142:143], v[156:157]
	s_waitcnt vmcnt(14)
; #define GAS __attribute__((address_space(1)))
; __device__ __forceinline__ unsigned pk2(float lo, float hi) { f32x2_t v = {lo, hi}; bf16x2_t b = __builtin_convertvector(v, bf16x2_t); return __builtin_bit_cast(unsigned, b); }
; #define U_LD(p) ({ const v2u w_ = *(const v2u*)(p); (f32x4){bflo(w_.x), bfhi(w_.x), bflo(w_.y), bfhi(w_.y)}; })
; __device__ __forceinline__ void p3_pool(Frame& F) {
;     ...
;                 if (s >= 0) n0 = U_LD(U + (mbase + s) * 512 + c0);
;                 if (i >= w && so >= 0) o0 = U_LD(U + (mbase + so) * 512 + c0);
;             } else {
;                 if (s >= 0) n0 = U_LD(U + (mbase + s) * 512 + c0); else n0 = *(const f32x4*)(state_pool + ((size_t)b * 15 + (s + 15)) * 512 + c0);
;                 if (i >= w) { if (so >= 0) o0 = U_LD(U + (mbase + so) * 512 + c0); else o0 = *(const f32x4*)(state_pool + ((size_t)b * 15 + (so + 15)) * 512 + c0); }
;             }
;             S0 += n0 - o0;
;             if (i >= 15) {
;                 const int cnt = isP ? (w < s + 1 ? w : s + 1) : w; const float inv = 1.f / (float)cnt;
;                 const f32x4 d0 = S0 * inv - n0;
;                 v2u wv; wv.x = pk2(d0[0], d0[1]); wv.y = pk2(d0[2], d0[3]);
;                 *(GAS v2u*)(D + (size_t)(c0 >> 8) * ((size_t)MT * 256) + (mbase + s) * 256 + (c0 & 255)) = wv;
;             }
;             if (!isP && s >= -7 && s < 0) *(GAS f32x4*)(out + O_POOLS + ((size_t)b * 15 + (s + 7)) * 512 + c0) = n0;
	global_store_dwordx4 v37, v[72:75], s[92:93]
	v_cndmask_b32_e64 v150, v64, v56, s[94:95]
	v_cndmask_b32_e64 v151, v65, v57, s[94:95]
	v_cndmask_b32_e64 v152, v66, v58, s[94:95]
	v_cndmask_b32_e64 v153, v67, v59, s[94:95]
	v_pk_add_f32 v[154:155], v[72:73], v[150:151] neg_lo:[0,1] neg_hi:[0,1]
	v_pk_add_f32 v[156:157], v[74:75], v[152:153] neg_lo:[0,1] neg_hi:[0,1]
	v_pk_add_f32 v[140:141], v[140:141], v[154:155]
	v_pk_add_f32 v[142:143], v[142:143], v[156:157]
	s_waitcnt vmcnt(14)
	global_store_dwordx4 v37, v[76:79], s[92:93] offset:2048
	s_add_u32 s92, s92, 0x1000
	s_addc_u32 s93, s93, 0
	v_cndmask_b32_e64 v150, v68, v60, s[94:95]
	v_cndmask_b32_e64 v151, v69, v61, s[94:95]
	v_cndmask_b32_e64 v152, v70, v62, s[94:95]
	v_cndmask_b32_e64 v153, v71, v63, s[94:95]
	v_pk_add_f32 v[154:155], v[76:77], v[150:151] neg_lo:[0,1] neg_hi:[0,1]
	v_pk_add_f32 v[156:157], v[78:79], v[152:153] neg_lo:[0,1] neg_hi:[0,1]
	v_pk_add_f32 v[140:141], v[140:141], v[154:155]
	v_pk_add_f32 v[142:143], v[142:143], v[156:157]
	s_waitcnt vmcnt(14)
	global_store_dwordx4 v37, v[80:83], s[92:93]
	v_cndmask_b32_e64 v150, v72, v64, s[94:95]
	v_cndmask_b32_e64 v151, v73, v65, s[94:95]
	v_cndmask_b32_e64 v152, v74, v66, s[94:95]
	v_cndmask_b32_e64 v153, v75, v67, s[94:95]
	v_pk_add_f32 v[154:155], v[80:81], v[150:151] neg_lo:[0,1] neg_hi:[0,1]
	v_pk_add_f32 v[156:157], v[82:83], v[152:153] neg_lo:[0,1] neg_hi:[0,1]
	v_pk_add_f32 v[140:141], v[140:141], v[154:155]
	v_pk_add_f32 v[142:143], v[142:143], v[156:157]
	s_waitcnt vmcnt(14)
	global_store_dwordx4 v37, v[84:87], s[92:93] offset:2048
	s_add_u32 s92, s92, 0x1000
	s_addc_u32 s93, s93, 0
	v_cndmask_b32_e64 v150, v76, v68, s[94:95]
	v_cndmask_b32_e64 v151, v77, v69, s[94:95]
	v_cndmask_b32_e64 v152, v78, v70, s[94:95]
	v_cndmask_b32_e64 v153, v79, v71, s[94:95]
	v_pk_add_f32 v[154:155], v[84:85], v[150:151] neg_lo:[0,1] neg_hi:[0,1]
	v_pk_add_f32 v[156:157], v[86:87], v[152:153] neg_lo:[0,1] neg_hi:[0,1]
	v_pk_add_f32 v[140:141], v[140:141], v[154:155]
	v_pk_add_f32 v[142:143], v[142:143], v[156:157]
	s_waitcnt vmcnt(14)
	global_store_dwordx4 v37, v[88:91], s[92:93]
	v_cndmask_b32_e64 v150, v80, v72, s[94:95]
	v_cndmask_b32_e64 v151, v81, v73, s[94:95]
	v_cndmask_b32_e64 v152, v82, v74, s[94:95]
	v_cndmask_b32_e64 v153, v83, v75, s[94:95]
	v_pk_add_f32 v[154:155], v[88:89], v[150:151] neg_lo:[0,1] neg_hi:[0,1]
	v_pk_add_f32 v[156:157], v[90:91], v[152:153] neg_lo:[0,1] neg_hi:[0,1]
	v_pk_add_f32 v[140:141], v[140:141], v[154:155]
	v_pk_add_f32 v[142:143], v[142:143], v[156:157]
	s_waitcnt vmcnt(14)
	global_store_dwordx4 v37, v[92:95], s[92:93] offset:2048
	s_add_u32 s92, s92, 0x1000
	s_addc_u32 s93, s93, 0
	v_cndmask_b32_e64 v150, v84, v76, s[94:95]
	v_cndmask_b32_e64 v151, v85, v77, s[94:95]
	v_cndmask_b32_e64 v152, v86, v78, s[94:95]
	v_cndmask_b32_e64 v153, v87, v79, s[94:95]
	v_pk_add_f32 v[154:155], v[92:93], v[150:151] neg_lo:[0,1] neg_hi:[0,1]
	v_pk_add_f32 v[156:157], v[94:95], v[152:153] neg_lo:[0,1] neg_hi:[0,1]
	v_pk_add_f32 v[140:141], v[140:141], v[154:155]
	v_pk_add_f32 v[142:143], v[142:143], v[156:157]
	s_waitcnt vmcnt(14)
	global_store_dwordx4 v37, v[96:99], s[92:93]
	v_cndmask_b32_e64 v150, v88, v80, s[94:95]
	v_cndmask_b32_e64 v151, v89, v81, s[94:95]
	v_cndmask_b32_e64 v152, v90, v82, s[94:95]
	v_cndmask_b32_e64 v153, v91, v83, s[94:95]
	v_pk_add_f32 v[154:155], v[96:97], v[150:151] neg_lo:[0,1] neg_hi:[0,1]
	v_pk_add_f32 v[156:157], v[98:99], v[152:153] neg_lo:[0,1] neg_hi:[0,1]
	v_pk_add_f32 v[140:141], v[140:141], v[154:155]
	v_pk_add_f32 v[142:143], v[142:143], v[156:157]
	s_waitcnt vmcnt(14)
	v_lshlrev_b32_e32 v176, 16, v100
	v_and_b32_e32 v177, 0xffff0000, v100
	v_lshlrev_b32_e32 v178, 16, v101
	v_and_b32_e32 v179, 0xffff0000, v101
	v_cndmask_b32_e64 v150, v92, v84, s[94:95]
	v_cndmask_b32_e64 v151, v93, v85, s[94:95]
	v_cndmask_b32_e64 v152, v94, v86, s[94:95]
	v_cndmask_b32_e64 v153, v95, v87, s[94:95]
	v_pk_add_f32 v[154:155], v[176:177], v[150:151] neg_lo:[0,1] neg_hi:[0,1]
	v_pk_add_f32 v[156:157], v[178:179], v[152:153] neg_lo:[0,1] neg_hi:[0,1]
	v_pk_add_f32 v[140:141], v[140:141], v[154:155]
	v_pk_add_f32 v[142:143], v[142:143], v[156:157]
	v_pk_fma_f32 v[158:159], v[164:165], v[140:141], v[176:177] op_sel_hi:[0,1,1] neg_lo:[0,0,1] neg_hi:[0,0,1]
	v_pk_fma_f32 v[160:161], v[164:165], v[142:143], v[178:179] op_sel_hi:[0,1,1] neg_lo:[0,0,1] neg_hi:[0,0,1]
	v_cvt_pk_bf16_f32 v162, v158, v159
	v_cvt_pk_bf16_f32 v163, v160, v161
	global_store_dwordx2 v36, v[162:163], s[84:85]
	s_waitcnt vmcnt(14)
	v_lshlrev_b32_e32 v180, 16, v102
	v_and_b32_e32 v181, 0xffff0000, v102
	v_lshlrev_b32_e32 v182, 16, v103
	v_and_b32_e32 v183, 0xffff0000, v103
	v_cndmask_b32_e64 v150, v96, v88, s[94:95]
	v_cndmask_b32_e64 v151, v97, v89, s[94:95]
	v_cndmask_b32_e64 v152, v98, v90, s[94:95]
	v_cndmask_b32_e64 v153, v99, v91, s[94:95]
	v_pk_add_f32 v[154:155], v[180:181], v[150:151] neg_lo:[0,1] neg_hi:[0,1]
	v_pk_add_f32 v[156:157], v[182:183], v[152:153] neg_lo:[0,1] neg_hi:[0,1]
	v_pk_add_f32 v[140:141], v[140:141], v[154:155]
	v_pk_add_f32 v[142:143], v[142:143], v[156:157]
	v_pk_fma_f32 v[158:159], v[164:165], v[140:141], v[180:181] op_sel_hi:[0,1,1] neg_lo:[0,0,1] neg_hi:[0,0,1]
	v_pk_fma_f32 v[160:161], v[164:165], v[142:143], v[182:183] op_sel_hi:[0,1,1] neg_lo:[0,0,1] neg_hi:[0,0,1]
	v_cvt_pk_bf16_f32 v162, v158, v159
	v_cvt_pk_bf16_f32 v163, v160, v161
	global_store_dwordx2 v36, v[162:163], s[84:85] offset:512
	s_waitcnt vmcnt(14)
; #define GAS __attribute__((address_space(1)))
; __device__ __forceinline__ unsigned pk2(float lo, float hi) { f32x2_t v = {lo, hi}; bf16x2_t b = __builtin_convertvector(v, bf16x2_t); return __builtin_bit_cast(unsigned, b); }
; #define U_LD(p) ({ const v2u w_ = *(const v2u*)(p); (f32x4){bflo(w_.x), bfhi(w_.x), bflo(w_.y), bfhi(w_.y)}; })
; __device__ __forceinline__ void p3_pool(Frame& F) {
;     ...
;         for (int i = 0; i < nsteps; ++i) {
;             const int s = s0 - 15 + i;
;             const int so = s - w;
;             f32x4 n0 = (f32x4){0.f, 0.f, 0.f, 0.f}, o0 = n0;
;             if (isP) {
;                 if (s >= 0) n0 = U_LD(U + (mbase + s) * 512 + c0);
;                 if (i >= w && so >= 0) o0 = U_LD(U + (mbase + so) * 512 + c0);
;             } else {
;                 if (s >= 0) n0 = U_LD(U + (mbase + s) * 512 + c0); else n0 = *(const f32x4*)(state_pool + ((size_t)b * 15 + (s + 15)) * 512 + c0);
;                 if (i >= w) { if (so >= 0) o0 = U_LD(U + (mbase + so) * 512 + c0); else o0 = *(const f32x4*)(state_pool + ((size_t)b * 15 + (so + 15)) * 512 + c0); }
;             }
;             S0 += n0 - o0;
;             if (i >= 15) {
;                 const int cnt = isP ? (w < s + 1 ? w : s + 1) : w; const float inv = 1.f / (float)cnt;
;                 const f32x4 d0 = S0 * inv - n0;
;                 v2u wv; wv.x = pk2(d0[0], d0[1]); wv.y = pk2(d0[2], d0[3]);
;                 *(GAS v2u*)(D + (size_t)(c0 >> 8) * ((size_t)MT * 256) + (mbase + s) * 256 + (c0 & 255)) = wv;
;             }
;             if (!isP && s >= -7 && s < 0) *(GAS f32x4*)(out + O_POOLS + ((size_t)b * 15 + (s + 7)) * 512 + c0) = n0;
	v_lshlrev_b32_e32 v184, 16, v104
	v_and_b32_e32 v185, 0xffff0000, v104
	v_lshlrev_b32_e32 v186, 16, v105
	v_and_b32_e32 v187, 0xffff0000, v105
	v_cndmask_b32_e64 v150, v176, v92, s[94:95]
	v_cndmask_b32_e64 v151, v177, v93, s[94:95]
	v_cndmask_b32_e64 v152, v178, v94, s[94:95]
	v_cndmask_b32_e64 v153, v179, v95, s[94:95]
	v_pk_add_f32 v[154:155], v[184:185], v[150:151] neg_lo:[0,1] neg_hi:[0,1]
	v_pk_add_f32 v[156:157], v[186:187], v[152:153] neg_lo:[0,1] neg_hi:[0,1]
	v_pk_add_f32 v[140:141], v[140:141], v[154:155]
	v_pk_add_f32 v[142:143], v[142:143], v[156:157]
	v_pk_fma_f32 v[158:159], v[164:165], v[140:141], v[184:185] op_sel_hi:[0,1,1] neg_lo:[0,0,1] neg_hi:[0,0,1]
	v_pk_fma_f32 v[160:161], v[164:165], v[142:143], v[186:187] op_sel_hi:[0,1,1] neg_lo:[0,0,1] neg_hi:[0,0,1]
	v_cvt_pk_bf16_f32 v162, v158, v159
	v_cvt_pk_bf16_f32 v163, v160, v161
	global_store_dwordx2 v36, v[162:163], s[84:85] offset:1024
	s_waitcnt vmcnt(14)
	v_lshlrev_b32_e32 v188, 16, v106
	v_and_b32_e32 v189, 0xffff0000, v106
	v_lshlrev_b32_e32 v190, 16, v107
	v_and_b32_e32 v191, 0xffff0000, v107
	v_cndmask_b32_e64 v150, v180, v96, s[94:95]
	v_cndmask_b32_e64 v151, v181, v97, s[94:95]
	v_cndmask_b32_e64 v152, v182, v98, s[94:95]
	v_cndmask_b32_e64 v153, v183, v99, s[94:95]
	v_pk_add_f32 v[154:155], v[188:189], v[150:151] neg_lo:[0,1] neg_hi:[0,1]
	v_pk_add_f32 v[156:157], v[190:191], v[152:153] neg_lo:[0,1] neg_hi:[0,1]
	v_pk_add_f32 v[140:141], v[140:141], v[154:155]
	v_pk_add_f32 v[142:143], v[142:143], v[156:157]
	v_pk_fma_f32 v[158:159], v[164:165], v[140:141], v[188:189] op_sel_hi:[0,1,1] neg_lo:[0,0,1] neg_hi:[0,0,1]
	v_pk_fma_f32 v[160:161], v[164:165], v[142:143], v[190:191] op_sel_hi:[0,1,1] neg_lo:[0,0,1] neg_hi:[0,0,1]
	v_cvt_pk_bf16_f32 v162, v158, v159
	v_cvt_pk_bf16_f32 v163, v160, v161
	global_store_dwordx2 v36, v[162:163], s[84:85] offset:1536
	s_waitcnt vmcnt(14)
	v_lshlrev_b32_e32 v192, 16, v108
	v_and_b32_e32 v193, 0xffff0000, v108
	v_lshlrev_b32_e32 v194, 16, v109
	v_and_b32_e32 v195, 0xffff0000, v109
	v_cndmask_b32_e64 v150, v184, v176, s[94:95]
	v_cndmask_b32_e64 v151, v185, v177, s[94:95]
	v_cndmask_b32_e64 v152, v186, v178, s[94:95]
	v_cndmask_b32_e64 v153, v187, v179, s[94:95]
	v_pk_add_f32 v[154:155], v[192:193], v[150:151] neg_lo:[0,1] neg_hi:[0,1]
	v_pk_add_f32 v[156:157], v[194:195], v[152:153] neg_lo:[0,1] neg_hi:[0,1]
	v_pk_add_f32 v[140:141], v[140:141], v[154:155]
	v_pk_add_f32 v[142:143], v[142:143], v[156:157]
	v_pk_fma_f32 v[158:159], v[164:165], v[140:141], v[192:193] op_sel_hi:[0,1,1] neg_lo:[0,0,1] neg_hi:[0,0,1]
	v_pk_fma_f32 v[160:161], v[164:165], v[142:143], v[194:195] op_sel_hi:[0,1,1] neg_lo:[0,0,1] neg_hi:[0,0,1]
	v_cvt_pk_bf16_f32 v162, v158, v159
	v_cvt_pk_bf16_f32 v163, v160, v161
	global_store_dwordx2 v36, v[162:163], s[84:85] offset:2048
	s_waitcnt vmcnt(14)
	v_lshlrev_b32_e32 v196, 16, v110
	v_and_b32_e32 v197, 0xffff0000, v110
	v_lshlrev_b32_e32 v198, 16, v111
	v_and_b32_e32 v199, 0xffff0000, v111
	v_cndmask_b32_e64 v150, v188, v180, s[94:95]
	v_cndmask_b32_e64 v151, v189, v181, s[94:95]
	v_cndmask_b32_e64 v152, v190, v182, s[94:95]
	v_cndmask_b32_e64 v153, v191, v183, s[94:95]
	v_pk_add_f32 v[154:155], v[196:197], v[150:151] neg_lo:[0,1] neg_hi:[0,1]
	v_pk_add_f32 v[156:157], v[198:199], v[152:153] neg_lo:[0,1] neg_hi:[0,1]
	v_pk_add_f32 v[140:141], v[140:141], v[154:155]
	v_pk_add_f32 v[142:143], v[142:143], v[156:157]
	v_pk_fma_f32 v[158:159], v[164:165], v[140:141], v[196:197] op_sel_hi:[0,1,1] neg_lo:[0,0,1] neg_hi:[0,0,1]
	v_pk_fma_f32 v[160:161], v[164:165], v[142:143], v[198:199] op_sel_hi:[0,1,1] neg_lo:[0,0,1] neg_hi:[0,0,1]
	v_cvt_pk_bf16_f32 v162, v158, v159
	v_cvt_pk_bf16_f32 v163, v160, v161
	global_store_dwordx2 v36, v[162:163], s[84:85] offset:2560
	s_waitcnt vmcnt(14)
	v_lshlrev_b32_e32 v200, 16, v112
	v_and_b32_e32 v201, 0xffff0000, v112
	v_lshlrev_b32_e32 v202, 16, v113
	v_and_b32_e32 v203, 0xffff0000, v113
	v_cndmask_b32_e64 v150, v192, v184, s[94:95]
	v_cndmask_b32_e64 v151, v193, v185, s[94:95]
	v_cndmask_b32_e64 v152, v194, v186, s[94:95]
	v_cndmask_b32_e64 v153, v195, v187, s[94:95]
	v_pk_add_f32 v[154:155], v[200:201], v[150:151] neg_lo:[0,1] neg_hi:[0,1]
	v_pk_add_f32 v[156:157], v[202:203], v[152:153] neg_lo:[0,1] neg_hi:[0,1]
	v_pk_add_f32 v[140:141], v[140:141], v[154:155]
	v_pk_add_f32 v[142:143], v[142:143], v[156:157]
	v_pk_fma_f32 v[158:159], v[164:165], v[140:141], v[200:201] op_sel_hi:[0,1,1] neg_lo:[0,0,1] neg_hi:[0,0,1]
	v_pk_fma_f32 v[160:161], v[164:165], v[142:143], v[202:203] op_sel_hi:[0,1,1] neg_lo:[0,0,1] neg_hi:[0,0,1]
	v_cvt_pk_bf16_f32 v162, v158, v159
	v_cvt_pk_bf16_f32 v163, v160, v161
	global_store_dwordx2 v36, v[162:163], s[84:85] offset:3072
	s_waitcnt vmcnt(14)
	v_lshlrev_b32_e32 v204, 16, v114
	v_and_b32_e32 v205, 0xffff0000, v114
	v_lshlrev_b32_e32 v206, 16, v115
	v_and_b32_e32 v207, 0xffff0000, v115
	v_cndmask_b32_e64 v150, v196, v188, s[94:95]
	v_cndmask_b32_e64 v151, v197, v189, s[94:95]
	v_cndmask_b32_e64 v152, v198, v190, s[94:95]
	v_cndmask_b32_e64 v153, v199, v191, s[94:95]
	v_pk_add_f32 v[154:155], v[204:205], v[150:151] neg_lo:[0,1] neg_hi:[0,1]
	v_pk_add_f32 v[156:157], v[206:207], v[152:153] neg_lo:[0,1] neg_hi:[0,1]
	v_pk_add_f32 v[140:141], v[140:141], v[154:155]
	v_pk_add_f32 v[142:143], v[142:143], v[156:157]
	v_pk_fma_f32 v[158:159], v[164:165], v[140:141], v[204:205] op_sel_hi:[0,1,1] neg_lo:[0,0,1] neg_hi:[0,0,1]
	v_pk_fma_f32 v[160:161], v[164:165], v[142:143], v[206:207] op_sel_hi:[0,1,1] neg_lo:[0,0,1] neg_hi:[0,0,1]
	v_cvt_pk_bf16_f32 v162, v158, v159
	v_cvt_pk_bf16_f32 v163, v160, v161
	global_store_dwordx2 v36, v[162:163], s[84:85] offset:3584
	s_branch .LBB0_515
; #define GAS __attribute__((address_space(1)))
; __device__ __forceinline__ unsigned pk2(float lo, float hi) { f32x2_t v = {lo, hi}; bf16x2_t b = __builtin_convertvector(v, bf16x2_t); return __builtin_bit_cast(unsigned, b); }
; #define U_LD(p) ({ const v2u w_ = *(const v2u*)(p); (f32x4){bflo(w_.x), bfhi(w_.x), bflo(w_.y), bfhi(w_.y)}; })
; __device__ __forceinline__ void p3_pool(Frame& F) {
;     ...
;         for (int i = 0; i < nsteps; ++i) {
;             const int s = s0 - 15 + i;
;             const int so = s - w;
;             f32x4 n0 = (f32x4){0.f, 0.f, 0.f, 0.f}, o0 = n0;
;             if (isP) {
;                 if (s >= 0) n0 = U_LD(U + (mbase + s) * 512 + c0);
;                 if (i >= w && so >= 0) o0 = U_LD(U + (mbase + so) * 512 + c0);
;             } else {
;                 if (s >= 0) n0 = U_LD(U + (mbase + s) * 512 + c0); else n0 = *(const f32x4*)(state_pool + ((size_t)b * 15 + (s + 15)) * 512 + c0);
;                 if (i >= w) { if (so >= 0) o0 = U_LD(U + (mbase + so) * 512 + c0); else o0 = *(const f32x4*)(state_pool + ((size_t)b * 15 + (so + 15)) * 512 + c0); }
;             }
;             S0 += n0 - o0;
;             if (i >= 15) {
;                 const int cnt = isP ? (w < s + 1 ? w : s + 1) : w; const float inv = 1.f / (float)cnt;
;                 const f32x4 d0 = S0 * inv - n0;
;                 v2u wv; wv.x = pk2(d0[0], d0[1]); wv.y = pk2(d0[2], d0[3]);
;                 *(GAS v2u*)(D + (size_t)(c0 >> 8) * ((size_t)MT * 256) + (mbase + s) * 256 + (c0 & 255)) = wv;
;             }
;             if (!isP && s >= -7 && s < 0) *(GAS f32x4*)(out + O_POOLS + ((size_t)b * 15 + (s + 7)) * 512 + c0) = n0;
.Lp3s_h1:
	v_mov_b32_e32 v140, 0
	v_mov_b32_e32 v141, 0
	v_mov_b32_e32 v142, 0
	v_mov_b32_e32 v143, 0
	v_mov_b32_e32 v166, 0
	v_mov_b32_e32 v167, 0
	v_mov_b32_e32 v168, 0
	v_mov_b32_e32 v169, 0
	v_mov_b32_e32 v144, 0x3e000000
	v_mov_b32_e32 v145, 0x3d800000
	v_cndmask_b32_e64 v164, v144, v145, s[94:95]
	s_waitcnt vmcnt(22)
	v_pk_add_f32 v[140:141], v[140:141], v[40:41]
	v_pk_add_f32 v[142:143], v[142:143], v[42:43]
	s_waitcnt vmcnt(21)
	v_pk_add_f32 v[140:141], v[140:141], v[44:45]
	v_pk_add_f32 v[142:143], v[142:143], v[46:47]
	s_waitcnt vmcnt(20)
	v_pk_add_f32 v[140:141], v[140:141], v[48:49]
	v_pk_add_f32 v[142:143], v[142:143], v[50:51]
	s_waitcnt vmcnt(19)
	v_pk_add_f32 v[140:141], v[140:141], v[52:53]
	v_pk_add_f32 v[142:143], v[142:143], v[54:55]
	s_waitcnt vmcnt(18)
	v_pk_add_f32 v[140:141], v[140:141], v[56:57]
	v_pk_add_f32 v[142:143], v[142:143], v[58:59]
	s_waitcnt vmcnt(17)
	v_pk_add_f32 v[140:141], v[140:141], v[60:61]
	v_pk_add_f32 v[142:143], v[142:143], v[62:63]
	s_waitcnt vmcnt(16)
	v_pk_add_f32 v[140:141], v[140:141], v[64:65]
	v_pk_add_f32 v[142:143], v[142:143], v[66:67]
	s_waitcnt vmcnt(15)
	v_pk_add_f32 v[140:141], v[140:141], v[68:69]
	v_pk_add_f32 v[142:143], v[142:143], v[70:71]
	s_waitcnt vmcnt(14)
	global_store_dwordx4 v37, v[72:75], s[92:93]
	v_cndmask_b32_e64 v150, v40, v166, s[94:95]
	v_cndmask_b32_e64 v151, v41, v167, s[94:95]
	v_cndmask_b32_e64 v152, v42, v168, s[94:95]
	v_cndmask_b32_e64 v153, v43, v169, s[94:95]
	v_pk_add_f32 v[154:155], v[72:73], v[150:151] neg_lo:[0,1] neg_hi:[0,1]
	v_pk_add_f32 v[156:157], v[74:75], v[152:153] neg_lo:[0,1] neg_hi:[0,1]
	v_pk_add_f32 v[140:141], v[140:141], v[154:155]
	v_pk_add_f32 v[142:143], v[142:143], v[156:157]
	s_waitcnt vmcnt(14)
	global_store_dwordx4 v37, v[76:79], s[92:93] offset:2048
	s_add_u32 s92, s92, 0x1000
	s_addc_u32 s93, s93, 0
	v_cndmask_b32_e64 v150, v44, v166, s[94:95]
	v_cndmask_b32_e64 v151, v45, v167, s[94:95]
	v_cndmask_b32_e64 v152, v46, v168, s[94:95]
	v_cndmask_b32_e64 v153, v47, v169, s[94:95]
	v_pk_add_f32 v[154:155], v[76:77], v[150:151] neg_lo:[0,1] neg_hi:[0,1]
	v_pk_add_f32 v[156:157], v[78:79], v[152:153] neg_lo:[0,1] neg_hi:[0,1]
	v_pk_add_f32 v[140:141], v[140:141], v[154:155]
	v_pk_add_f32 v[142:143], v[142:143], v[156:157]
	s_waitcnt vmcnt(14)
	global_store_dwordx4 v37, v[80:83], s[92:93]
	v_cndmask_b32_e64 v150, v48, v166, s[94:95]
	v_cndmask_b32_e64 v151, v49, v167, s[94:95]
	v_cndmask_b32_e64 v152, v50, v168, s[94:95]
	v_cndmask_b32_e64 v153, v51, v169, s[94:95]
	v_pk_add_f32 v[154:155], v[80:81], v[150:151] neg_lo:[0,1] neg_hi:[0,1]
	v_pk_add_f32 v[156:157], v[82:83], v[152:153] neg_lo:[0,1] neg_hi:[0,1]
	v_pk_add_f32 v[140:141], v[140:141], v[154:155]
	v_pk_add_f32 v[142:143], v[142:143], v[156:157]
	s_waitcnt vmcnt(14)
	global_store_dwordx4 v37, v[84:87], s[92:93] offset:2048
	s_add_u32 s92, s92, 0x1000
	s_addc_u32 s93, s93, 0
	v_cndmask_b32_e64 v150, v52, v166, s[94:95]
	v_cndmask_b32_e64 v151, v53, v167, s[94:95]
	v_cndmask_b32_e64 v152, v54, v168, s[94:95]
	v_cndmask_b32_e64 v153, v55, v169, s[94:95]
	v_pk_add_f32 v[154:155], v[84:85], v[150:151] neg_lo:[0,1] neg_hi:[0,1]
	v_pk_add_f32 v[156:157], v[86:87], v[152:153] neg_lo:[0,1] neg_hi:[0,1]
	v_pk_add_f32 v[140:141], v[140:141], v[154:155]
	v_pk_add_f32 v[142:143], v[142:143], v[156:157]
	s_waitcnt vmcnt(14)
	global_store_dwordx4 v37, v[88:91], s[92:93]
	v_cndmask_b32_e64 v150, v56, v166, s[94:95]
	v_cndmask_b32_e64 v151, v57, v167, s[94:95]
	v_cndmask_b32_e64 v152, v58, v168, s[94:95]
	v_cndmask_b32_e64 v153, v59, v169, s[94:95]
	v_pk_add_f32 v[154:155], v[88:89], v[150:151] neg_lo:[0,1] neg_hi:[0,1]
	v_pk_add_f32 v[156:157], v[90:91], v[152:153] neg_lo:[0,1] neg_hi:[0,1]
	v_pk_add_f32 v[140:141], v[140:141], v[154:155]
	v_pk_add_f32 v[142:143], v[142:143], v[156:157]
	s_waitcnt vmcnt(14)
	global_store_dwordx4 v37, v[92:95], s[92:93] offset:2048
	s_add_u32 s92, s92, 0x1000
	s_addc_u32 s93, s93, 0
	v_cndmask_b32_e64 v150, v60, v166, s[94:95]
	v_cndmask_b32_e64 v151, v61, v167, s[94:95]
	v_cndmask_b32_e64 v152, v62, v168, s[94:95]
	v_cndmask_b32_e64 v153, v63, v169, s[94:95]
	v_pk_add_f32 v[154:155], v[92:93], v[150:151] neg_lo:[0,1] neg_hi:[0,1]
	v_pk_add_f32 v[156:157], v[94:95], v[152:153] neg_lo:[0,1] neg_hi:[0,1]
	v_pk_add_f32 v[140:141], v[140:141], v[154:155]
	v_pk_add_f32 v[142:143], v[142:143], v[156:157]
	s_waitcnt vmcnt(14)
	global_store_dwordx4 v37, v[96:99], s[92:93]
	v_cndmask_b32_e64 v150, v64, v166, s[94:95]
	v_cndmask_b32_e64 v151, v65, v167, s[94:95]
	v_cndmask_b32_e64 v152, v66, v168, s[94:95]
	v_cndmask_b32_e64 v153, v67, v169, s[94:95]
	v_pk_add_f32 v[154:155], v[96:97], v[150:151] neg_lo:[0,1] neg_hi:[0,1]
	v_pk_add_f32 v[156:157], v[98:99], v[152:153] neg_lo:[0,1] neg_hi:[0,1]
	v_pk_add_f32 v[140:141], v[140:141], v[154:155]
	v_pk_add_f32 v[142:143], v[142:143], v[156:157]
	s_waitcnt vmcnt(14)
	v_lshlrev_b32_e32 v176, 16, v100
	v_and_b32_e32 v177, 0xffff0000, v100
	v_lshlrev_b32_e32 v178, 16, v101
	v_and_b32_e32 v179, 0xffff0000, v101
	v_cndmask_b32_e64 v150, v68, v166, s[94:95]
	v_cndmask_b32_e64 v151, v69, v167, s[94:95]
	v_cndmask_b32_e64 v152, v70, v168, s[94:95]
	v_cndmask_b32_e64 v153, v71, v169, s[94:95]
	v_pk_add_f32 v[154:155], v[176:177], v[150:151] neg_lo:[0,1] neg_hi:[0,1]
	v_pk_add_f32 v[156:157], v[178:179], v[152:153] neg_lo:[0,1] neg_hi:[0,1]
	v_pk_add_f32 v[140:141], v[140:141], v[154:155]
	v_pk_add_f32 v[142:143], v[142:143], v[156:157]
	v_pk_fma_f32 v[158:159], v[164:165], v[140:141], v[176:177] op_sel_hi:[0,1,1] neg_lo:[0,0,1] neg_hi:[0,0,1]
	v_pk_fma_f32 v[160:161], v[164:165], v[142:143], v[178:179] op_sel_hi:[0,1,1] neg_lo:[0,0,1] neg_hi:[0,0,1]
	v_cvt_pk_bf16_f32 v162, v158, v159
	v_cvt_pk_bf16_f32 v163, v160, v161
	global_store_dwordx2 v36, v[162:163], s[84:85]
	s_waitcnt vmcnt(14)
; #define GAS __attribute__((address_space(1)))
; __device__ __forceinline__ unsigned pk2(float lo, float hi) { f32x2_t v = {lo, hi}; bf16x2_t b = __builtin_convertvector(v, bf16x2_t); return __builtin_bit_cast(unsigned, b); }
; #define U_LD(p) ({ const v2u w_ = *(const v2u*)(p); (f32x4){bflo(w_.x), bfhi(w_.x), bflo(w_.y), bfhi(w_.y)}; })
; __device__ __forceinline__ void p3_pool(Frame& F) {
;     ...
;         for (int i = 0; i < nsteps; ++i) {
;             const int s = s0 - 15 + i;
;             const int so = s - w;
;             f32x4 n0 = (f32x4){0.f, 0.f, 0.f, 0.f}, o0 = n0;
;             if (isP) {
;                 if (s >= 0) n0 = U_LD(U + (mbase + s) * 512 + c0);
;                 if (i >= w && so >= 0) o0 = U_LD(U + (mbase + so) * 512 + c0);
;             } else {
;                 if (s >= 0) n0 = U_LD(U + (mbase + s) * 512 + c0); else n0 = *(const f32x4*)(state_pool + ((size_t)b * 15 + (s + 15)) * 512 + c0);
;                 if (i >= w) { if (so >= 0) o0 = U_LD(U + (mbase + so) * 512 + c0); else o0 = *(const f32x4*)(state_pool + ((size_t)b * 15 + (so + 15)) * 512 + c0); }
;             }
;             S0 += n0 - o0;
;             if (i >= 15) {
;                 const int cnt = isP ? (w < s + 1 ? w : s + 1) : w; const float inv = 1.f / (float)cnt;
;                 const f32x4 d0 = S0 * inv - n0;
;                 v2u wv; wv.x = pk2(d0[0], d0[1]); wv.y = pk2(d0[2], d0[3]);
;                 *(GAS v2u*)(D + (size_t)(c0 >> 8) * ((size_t)MT * 256) + (mbase + s) * 256 + (c0 & 255)) = wv;
;             }
;             if (!isP && s >= -7 && s < 0) *(GAS f32x4*)(out + O_POOLS + ((size_t)b * 15 + (s + 7)) * 512 + c0) = n0;
	v_lshlrev_b32_e32 v180, 16, v102
	v_and_b32_e32 v181, 0xffff0000, v102
	v_lshlrev_b32_e32 v182, 16, v103
	v_and_b32_e32 v183, 0xffff0000, v103
	v_cndmask_b32_e64 v150, v72, v40, s[94:95]
	v_cndmask_b32_e64 v151, v73, v41, s[94:95]
	v_cndmask_b32_e64 v152, v74, v42, s[94:95]
	v_cndmask_b32_e64 v153, v75, v43, s[94:95]
	v_pk_add_f32 v[154:155], v[180:181], v[150:151] neg_lo:[0,1] neg_hi:[0,1]
	v_pk_add_f32 v[156:157], v[182:183], v[152:153] neg_lo:[0,1] neg_hi:[0,1]
	v_pk_add_f32 v[140:141], v[140:141], v[154:155]
	v_pk_add_f32 v[142:143], v[142:143], v[156:157]
	v_pk_fma_f32 v[158:159], v[164:165], v[140:141], v[180:181] op_sel_hi:[0,1,1] neg_lo:[0,0,1] neg_hi:[0,0,1]
	v_pk_fma_f32 v[160:161], v[164:165], v[142:143], v[182:183] op_sel_hi:[0,1,1] neg_lo:[0,0,1] neg_hi:[0,0,1]
	v_cvt_pk_bf16_f32 v162, v158, v159
	v_cvt_pk_bf16_f32 v163, v160, v161
	global_store_dwordx2 v36, v[162:163], s[84:85] offset:512
	s_waitcnt vmcnt(14)
	v_lshlrev_b32_e32 v184, 16, v104
	v_and_b32_e32 v185, 0xffff0000, v104
	v_lshlrev_b32_e32 v186, 16, v105
	v_and_b32_e32 v187, 0xffff0000, v105
	v_cndmask_b32_e64 v150, v76, v44, s[94:95]
	v_cndmask_b32_e64 v151, v77, v45, s[94:95]
	v_cndmask_b32_e64 v152, v78, v46, s[94:95]
	v_cndmask_b32_e64 v153, v79, v47, s[94:95]
	v_pk_add_f32 v[154:155], v[184:185], v[150:151] neg_lo:[0,1] neg_hi:[0,1]
	v_pk_add_f32 v[156:157], v[186:187], v[152:153] neg_lo:[0,1] neg_hi:[0,1]
	v_pk_add_f32 v[140:141], v[140:141], v[154:155]
	v_pk_add_f32 v[142:143], v[142:143], v[156:157]
	v_pk_fma_f32 v[158:159], v[164:165], v[140:141], v[184:185] op_sel_hi:[0,1,1] neg_lo:[0,0,1] neg_hi:[0,0,1]
	v_pk_fma_f32 v[160:161], v[164:165], v[142:143], v[186:187] op_sel_hi:[0,1,1] neg_lo:[0,0,1] neg_hi:[0,0,1]
	v_cvt_pk_bf16_f32 v162, v158, v159
	v_cvt_pk_bf16_f32 v163, v160, v161
	global_store_dwordx2 v36, v[162:163], s[84:85] offset:1024
	s_waitcnt vmcnt(14)
	v_lshlrev_b32_e32 v188, 16, v106
	v_and_b32_e32 v189, 0xffff0000, v106
	v_lshlrev_b32_e32 v190, 16, v107
	v_and_b32_e32 v191, 0xffff0000, v107
	v_cndmask_b32_e64 v150, v80, v48, s[94:95]
	v_cndmask_b32_e64 v151, v81, v49, s[94:95]
	v_cndmask_b32_e64 v152, v82, v50, s[94:95]
	v_cndmask_b32_e64 v153, v83, v51, s[94:95]
	v_pk_add_f32 v[154:155], v[188:189], v[150:151] neg_lo:[0,1] neg_hi:[0,1]
	v_pk_add_f32 v[156:157], v[190:191], v[152:153] neg_lo:[0,1] neg_hi:[0,1]
	v_pk_add_f32 v[140:141], v[140:141], v[154:155]
	v_pk_add_f32 v[142:143], v[142:143], v[156:157]
	v_pk_fma_f32 v[158:159], v[164:165], v[140:141], v[188:189] op_sel_hi:[0,1,1] neg_lo:[0,0,1] neg_hi:[0,0,1]
	v_pk_fma_f32 v[160:161], v[164:165], v[142:143], v[190:191] op_sel_hi:[0,1,1] neg_lo:[0,0,1] neg_hi:[0,0,1]
	v_cvt_pk_bf16_f32 v162, v158, v159
	v_cvt_pk_bf16_f32 v163, v160, v161
	global_store_dwordx2 v36, v[162:163], s[84:85] offset:1536
	s_waitcnt vmcnt(14)
	v_lshlrev_b32_e32 v192, 16, v108
	v_and_b32_e32 v193, 0xffff0000, v108
	v_lshlrev_b32_e32 v194, 16, v109
	v_and_b32_e32 v195, 0xffff0000, v109
	v_cndmask_b32_e64 v150, v84, v52, s[94:95]
	v_cndmask_b32_e64 v151, v85, v53, s[94:95]
	v_cndmask_b32_e64 v152, v86, v54, s[94:95]
	v_cndmask_b32_e64 v153, v87, v55, s[94:95]
	v_pk_add_f32 v[154:155], v[192:193], v[150:151] neg_lo:[0,1] neg_hi:[0,1]
	v_pk_add_f32 v[156:157], v[194:195], v[152:153] neg_lo:[0,1] neg_hi:[0,1]
	v_pk_add_f32 v[140:141], v[140:141], v[154:155]
	v_pk_add_f32 v[142:143], v[142:143], v[156:157]
	v_pk_fma_f32 v[158:159], v[164:165], v[140:141], v[192:193] op_sel_hi:[0,1,1] neg_lo:[0,0,1] neg_hi:[0,0,1]
	v_pk_fma_f32 v[160:161], v[164:165], v[142:143], v[194:195] op_sel_hi:[0,1,1] neg_lo:[0,0,1] neg_hi:[0,0,1]
	v_cvt_pk_bf16_f32 v162, v158, v159
	v_cvt_pk_bf16_f32 v163, v160, v161
	global_store_dwordx2 v36, v[162:163], s[84:85] offset:2048
	s_waitcnt vmcnt(14)
	v_lshlrev_b32_e32 v196, 16, v110
	v_and_b32_e32 v197, 0xffff0000, v110
	v_lshlrev_b32_e32 v198, 16, v111
	v_and_b32_e32 v199, 0xffff0000, v111
	v_cndmask_b32_e64 v150, v88, v56, s[94:95]
	v_cndmask_b32_e64 v151, v89, v57, s[94:95]
	v_cndmask_b32_e64 v152, v90, v58, s[94:95]
	v_cndmask_b32_e64 v153, v91, v59, s[94:95]
	v_pk_add_f32 v[154:155], v[196:197], v[150:151] neg_lo:[0,1] neg_hi:[0,1]
	v_pk_add_f32 v[156:157], v[198:199], v[152:153] neg_lo:[0,1] neg_hi:[0,1]
	v_pk_add_f32 v[140:141], v[140:141], v[154:155]
	v_pk_add_f32 v[142:143], v[142:143], v[156:157]
	v_pk_fma_f32 v[158:159], v[164:165], v[140:141], v[196:197] op_sel_hi:[0,1,1] neg_lo:[0,0,1] neg_hi:[0,0,1]
	v_pk_fma_f32 v[160:161], v[164:165], v[142:143], v[198:199] op_sel_hi:[0,1,1] neg_lo:[0,0,1] neg_hi:[0,0,1]
	v_cvt_pk_bf16_f32 v162, v158, v159
	v_cvt_pk_bf16_f32 v163, v160, v161
	global_store_dwordx2 v36, v[162:163], s[84:85] offset:2560
	s_waitcnt vmcnt(14)
	v_lshlrev_b32_e32 v200, 16, v112
	v_and_b32_e32 v201, 0xffff0000, v112
	v_lshlrev_b32_e32 v202, 16, v113
	v_and_b32_e32 v203, 0xffff0000, v113
	v_cndmask_b32_e64 v150, v92, v60, s[94:95]
	v_cndmask_b32_e64 v151, v93, v61, s[94:95]
	v_cndmask_b32_e64 v152, v94, v62, s[94:95]
	v_cndmask_b32_e64 v153, v95, v63, s[94:95]
	v_pk_add_f32 v[154:155], v[200:201], v[150:151] neg_lo:[0,1] neg_hi:[0,1]
	v_pk_add_f32 v[156:157], v[202:203], v[152:153] neg_lo:[0,1] neg_hi:[0,1]
	v_pk_add_f32 v[140:141], v[140:141], v[154:155]
	v_pk_add_f32 v[142:143], v[142:143], v[156:157]
	v_pk_fma_f32 v[158:159], v[164:165], v[140:141], v[200:201] op_sel_hi:[0,1,1] neg_lo:[0,0,1] neg_hi:[0,0,1]
	v_pk_fma_f32 v[160:161], v[164:165], v[142:143], v[202:203] op_sel_hi:[0,1,1] neg_lo:[0,0,1] neg_hi:[0,0,1]
	v_cvt_pk_bf16_f32 v162, v158, v159
	v_cvt_pk_bf16_f32 v163, v160, v161
	global_store_dwordx2 v36, v[162:163], s[84:85] offset:3072
	s_waitcnt vmcnt(14)
	v_lshlrev_b32_e32 v204, 16, v114
	v_and_b32_e32 v205, 0xffff0000, v114
	v_lshlrev_b32_e32 v206, 16, v115
	v_and_b32_e32 v207, 0xffff0000, v115
	v_cndmask_b32_e64 v150, v96, v64, s[94:95]
	v_cndmask_b32_e64 v151, v97, v65, s[94:95]
	v_cndmask_b32_e64 v152, v98, v66, s[94:95]
	v_cndmask_b32_e64 v153, v99, v67, s[94:95]
	v_pk_add_f32 v[154:155], v[204:205], v[150:151] neg_lo:[0,1] neg_hi:[0,1]
	v_pk_add_f32 v[156:157], v[206:207], v[152:153] neg_lo:[0,1] neg_hi:[0,1]
	v_pk_add_f32 v[140:141], v[140:141], v[154:155]
	v_pk_add_f32 v[142:143], v[142:143], v[156:157]
	v_pk_fma_f32 v[158:159], v[164:165], v[140:141], v[204:205] op_sel_hi:[0,1,1] neg_lo:[0,0,1] neg_hi:[0,0,1]
	v_pk_fma_f32 v[160:161], v[164:165], v[142:143], v[206:207] op_sel_hi:[0,1,1] neg_lo:[0,0,1] neg_hi:[0,0,1]
	v_cvt_pk_bf16_f32 v162, v158, v159
	v_cvt_pk_bf16_f32 v163, v160, v161
	global_store_dwordx2 v36, v[162:163], s[84:85] offset:3584
	s_branch .LBB0_515
